# hand-scheduled branch-free SWIGLU epilogue (packed f32, exp/rcp), on top of fast division
# baseline (speedup 1.0000x reference)
.Lswiglu_fast:
	s_lshl_b32 s4, s65, 7
	v_subrev_u32_e32 v146, s4, v162
	v_readlane_b32 s4, v253, 35
	v_readlane_b32 s5, v253, 28
	v_mov_b32_e32 v168, s4
	v_mov_b32_e32 v169, s5
	ds_read_b64 v[148:149], v168
	ds_read_b32 v170, v169
	v_ashrrev_i32_e32 v147, 31, v146
	v_mov_b32_e32 v176, 0xbfb8aa3b
	v_mov_b32_e32 v177, 0xbfb8aa3b
	s_waitcnt lgkmcnt(0)
	v_readfirstlane_b32 s5, v170
	v_mad_i64_i32 v[172:173], s[2:3], v170, v160, 0
	v_lshl_add_u64 v[174:175], v[146:147], 1, v[148:149]
	v_lshl_add_u64 v[172:173], v[172:173], 1, v[174:175]
	s_lshl_b32 s6, s5, 5
	s_mov_b32 s7, 0
	s_mul_i32 s8, s6, 5
	s_mov_b32 s9, 0
	v_pk_mul_f32 v[206:207], v[126:127], v[176:177]
	v_pk_mul_f32 v[208:209], v[128:129], v[176:177]
	v_pk_mul_f32 v[210:211], v[118:119], v[176:177]
	v_pk_mul_f32 v[212:213], v[120:121], v[176:177]
	v_exp_f32_e32 v206, v206
	v_exp_f32_e32 v207, v207
	v_exp_f32_e32 v208, v208
	v_exp_f32_e32 v209, v209
	v_exp_f32_e32 v210, v210
	v_exp_f32_e32 v211, v211
	v_exp_f32_e32 v212, v212
	v_exp_f32_e32 v213, v213
	v_pk_mul_f32 v[214:215], v[126:127], v[122:123]
	v_pk_mul_f32 v[216:217], v[128:129], v[124:125]
	v_pk_add_f32 v[206:207], v[206:207], 1.0 op_sel_hi:[1,0]
	v_pk_add_f32 v[208:209], v[208:209], 1.0 op_sel_hi:[1,0]
	v_pk_add_f32 v[210:211], v[210:211], 1.0 op_sel_hi:[1,0]
	v_pk_add_f32 v[212:213], v[212:213], 1.0 op_sel_hi:[1,0]
	v_rcp_f32_e32 v206, v206
	v_rcp_f32_e32 v207, v207
	v_rcp_f32_e32 v208, v208
	v_rcp_f32_e32 v209, v209
	v_rcp_f32_e32 v210, v210
	v_rcp_f32_e32 v211, v211
	v_rcp_f32_e32 v212, v212
	v_rcp_f32_e32 v213, v213
	v_pk_mul_f32 v[218:219], v[118:119], v[114:115]
	v_pk_mul_f32 v[220:221], v[120:121], v[116:117]
	v_pk_mul_f32 v[214:215], v[214:215], v[206:207]
	v_pk_mul_f32 v[216:217], v[216:217], v[208:209]
	v_pk_mul_f32 v[218:219], v[218:219], v[210:211]
	v_pk_mul_f32 v[220:221], v[220:221], v[212:213]
	v_cvt_pk_bf16_f32 v222, v214, v215
	v_cvt_pk_bf16_f32 v223, v216, v217
	v_cvt_pk_bf16_f32 v224, v218, v219
	v_cvt_pk_bf16_f32 v225, v220, v221
	global_store_dwordx2 v[172:173], v[222:223], off
	global_store_dwordx2 v[172:173], v[224:225], off offset:32
	v_lshl_add_u64 v[172:173], v[172:173], 0, s[6:7]
	v_pk_mul_f32 v[130:131], v[110:111], v[176:177]
	v_pk_mul_f32 v[132:133], v[112:113], v[176:177]
	v_pk_mul_f32 v[134:135], v[102:103], v[176:177]
	v_pk_mul_f32 v[136:137], v[104:105], v[176:177]
	v_exp_f32_e32 v130, v130
	v_exp_f32_e32 v131, v131
	v_exp_f32_e32 v132, v132
	v_exp_f32_e32 v133, v133
	v_exp_f32_e32 v134, v134
	v_exp_f32_e32 v135, v135
	v_exp_f32_e32 v136, v136
	v_exp_f32_e32 v137, v137
	v_pk_mul_f32 v[138:139], v[110:111], v[106:107]
	v_pk_mul_f32 v[140:141], v[112:113], v[108:109]
	v_pk_add_f32 v[130:131], v[130:131], 1.0 op_sel_hi:[1,0]
	v_pk_add_f32 v[132:133], v[132:133], 1.0 op_sel_hi:[1,0]
	v_pk_add_f32 v[134:135], v[134:135], 1.0 op_sel_hi:[1,0]
	v_pk_add_f32 v[136:137], v[136:137], 1.0 op_sel_hi:[1,0]
	v_rcp_f32_e32 v130, v130
	v_rcp_f32_e32 v131, v131
	v_rcp_f32_e32 v132, v132
	v_rcp_f32_e32 v133, v133
	v_rcp_f32_e32 v134, v134
	v_rcp_f32_e32 v135, v135
	v_rcp_f32_e32 v136, v136
	v_rcp_f32_e32 v137, v137
	v_pk_mul_f32 v[142:143], v[102:103], v[98:99]
	v_pk_mul_f32 v[144:145], v[104:105], v[100:101]
	v_pk_mul_f32 v[138:139], v[138:139], v[130:131]
	v_pk_mul_f32 v[140:141], v[140:141], v[132:133]
	v_pk_mul_f32 v[142:143], v[142:143], v[134:135]
	v_pk_mul_f32 v[144:145], v[144:145], v[136:137]
	v_cvt_pk_bf16_f32 v164, v138, v139
	v_cvt_pk_bf16_f32 v165, v140, v141
	v_cvt_pk_bf16_f32 v166, v142, v143
	v_cvt_pk_bf16_f32 v167, v144, v145
	global_store_dwordx2 v[172:173], v[164:165], off
	global_store_dwordx2 v[172:173], v[166:167], off offset:32
	v_lshl_add_u64 v[172:173], v[172:173], 0, s[6:7]
	v_pk_mul_f32 v[206:207], v[94:95], v[176:177]
	v_pk_mul_f32 v[208:209], v[96:97], v[176:177]
	v_pk_mul_f32 v[210:211], v[86:87], v[176:177]
	v_pk_mul_f32 v[212:213], v[88:89], v[176:177]
	v_exp_f32_e32 v206, v206
	v_exp_f32_e32 v207, v207
	v_exp_f32_e32 v208, v208
	v_exp_f32_e32 v209, v209
	v_exp_f32_e32 v210, v210
	v_exp_f32_e32 v211, v211
	v_exp_f32_e32 v212, v212
	v_exp_f32_e32 v213, v213
	v_pk_mul_f32 v[214:215], v[94:95], v[90:91]
	v_pk_mul_f32 v[216:217], v[96:97], v[92:93]
	v_pk_add_f32 v[206:207], v[206:207], 1.0 op_sel_hi:[1,0]
	v_pk_add_f32 v[208:209], v[208:209], 1.0 op_sel_hi:[1,0]
	v_pk_add_f32 v[210:211], v[210:211], 1.0 op_sel_hi:[1,0]
	v_pk_add_f32 v[212:213], v[212:213], 1.0 op_sel_hi:[1,0]
	v_rcp_f32_e32 v206, v206
	v_rcp_f32_e32 v207, v207
	v_rcp_f32_e32 v208, v208
	v_rcp_f32_e32 v209, v209
	v_rcp_f32_e32 v210, v210
	v_rcp_f32_e32 v211, v211
	v_rcp_f32_e32 v212, v212
	v_rcp_f32_e32 v213, v213
	v_pk_mul_f32 v[218:219], v[86:87], v[82:83]
	v_pk_mul_f32 v[220:221], v[88:89], v[84:85]
	v_pk_mul_f32 v[214:215], v[214:215], v[206:207]
	v_pk_mul_f32 v[216:217], v[216:217], v[208:209]
	v_pk_mul_f32 v[218:219], v[218:219], v[210:211]
	v_pk_mul_f32 v[220:221], v[220:221], v[212:213]
	v_cvt_pk_bf16_f32 v222, v214, v215
	v_cvt_pk_bf16_f32 v223, v216, v217
	v_cvt_pk_bf16_f32 v224, v218, v219
	v_cvt_pk_bf16_f32 v225, v220, v221
	global_store_dwordx2 v[172:173], v[222:223], off
	global_store_dwordx2 v[172:173], v[224:225], off offset:32
	v_lshl_add_u64 v[172:173], v[172:173], 0, s[6:7]
	v_pk_mul_f32 v[130:131], v[78:79], v[176:177]
	v_pk_mul_f32 v[132:133], v[80:81], v[176:177]
	v_pk_mul_f32 v[134:135], v[70:71], v[176:177]
	v_pk_mul_f32 v[136:137], v[72:73], v[176:177]
	v_exp_f32_e32 v130, v130
	v_exp_f32_e32 v131, v131
	v_exp_f32_e32 v132, v132
	v_exp_f32_e32 v133, v133
	v_exp_f32_e32 v134, v134
	v_exp_f32_e32 v135, v135
	v_exp_f32_e32 v136, v136
	v_exp_f32_e32 v137, v137
	v_pk_mul_f32 v[138:139], v[78:79], v[74:75]
	v_pk_mul_f32 v[140:141], v[80:81], v[76:77]
	v_pk_add_f32 v[130:131], v[130:131], 1.0 op_sel_hi:[1,0]
	v_pk_add_f32 v[132:133], v[132:133], 1.0 op_sel_hi:[1,0]
	v_pk_add_f32 v[134:135], v[134:135], 1.0 op_sel_hi:[1,0]
	v_pk_add_f32 v[136:137], v[136:137], 1.0 op_sel_hi:[1,0]
	v_rcp_f32_e32 v130, v130
	v_rcp_f32_e32 v131, v131
	v_rcp_f32_e32 v132, v132
	v_rcp_f32_e32 v133, v133
	v_rcp_f32_e32 v134, v134
	v_rcp_f32_e32 v135, v135
	v_rcp_f32_e32 v136, v136
	v_rcp_f32_e32 v137, v137
	v_pk_mul_f32 v[142:143], v[70:71], v[66:67]
	v_pk_mul_f32 v[144:145], v[72:73], v[68:69]
	v_pk_mul_f32 v[138:139], v[138:139], v[130:131]
	v_pk_mul_f32 v[140:141], v[140:141], v[132:133]
	v_pk_mul_f32 v[142:143], v[142:143], v[134:135]
	v_pk_mul_f32 v[144:145], v[144:145], v[136:137]
	v_cvt_pk_bf16_f32 v164, v138, v139
	v_cvt_pk_bf16_f32 v165, v140, v141
	v_cvt_pk_bf16_f32 v166, v142, v143
	v_cvt_pk_bf16_f32 v167, v144, v145
	global_store_dwordx2 v[172:173], v[164:165], off
	global_store_dwordx2 v[172:173], v[166:167], off offset:32
	v_lshl_add_u64 v[172:173], v[172:173], 0, s[8:9]
	v_pk_mul_f32 v[206:207], v[62:63], v[176:177]
	v_pk_mul_f32 v[208:209], v[64:65], v[176:177]
	v_pk_mul_f32 v[210:211], v[54:55], v[176:177]
	v_pk_mul_f32 v[212:213], v[56:57], v[176:177]
	v_exp_f32_e32 v206, v206
	v_exp_f32_e32 v207, v207
	v_exp_f32_e32 v208, v208
	v_exp_f32_e32 v209, v209
	v_exp_f32_e32 v210, v210
	v_exp_f32_e32 v211, v211
	v_exp_f32_e32 v212, v212
	v_exp_f32_e32 v213, v213
	v_pk_mul_f32 v[214:215], v[62:63], v[58:59]
	v_pk_mul_f32 v[216:217], v[64:65], v[60:61]
	v_pk_add_f32 v[206:207], v[206:207], 1.0 op_sel_hi:[1,0]
	v_pk_add_f32 v[208:209], v[208:209], 1.0 op_sel_hi:[1,0]
	v_pk_add_f32 v[210:211], v[210:211], 1.0 op_sel_hi:[1,0]
	v_pk_add_f32 v[212:213], v[212:213], 1.0 op_sel_hi:[1,0]
	v_rcp_f32_e32 v206, v206
	v_rcp_f32_e32 v207, v207
	v_rcp_f32_e32 v208, v208
	v_rcp_f32_e32 v209, v209
	v_rcp_f32_e32 v210, v210
	v_rcp_f32_e32 v211, v211
	v_rcp_f32_e32 v212, v212
	v_rcp_f32_e32 v213, v213
	v_pk_mul_f32 v[218:219], v[54:55], v[50:51]
	v_pk_mul_f32 v[220:221], v[56:57], v[52:53]
	v_pk_mul_f32 v[214:215], v[214:215], v[206:207]
	v_pk_mul_f32 v[216:217], v[216:217], v[208:209]
	v_pk_mul_f32 v[218:219], v[218:219], v[210:211]
	v_pk_mul_f32 v[220:221], v[220:221], v[212:213]
	v_cvt_pk_bf16_f32 v222, v214, v215
	v_cvt_pk_bf16_f32 v223, v216, v217
	v_cvt_pk_bf16_f32 v224, v218, v219
	v_cvt_pk_bf16_f32 v225, v220, v221
	global_store_dwordx2 v[172:173], v[222:223], off
	global_store_dwordx2 v[172:173], v[224:225], off offset:32
	v_lshl_add_u64 v[172:173], v[172:173], 0, s[6:7]
	v_pk_mul_f32 v[130:131], v[46:47], v[176:177]
	v_pk_mul_f32 v[132:133], v[48:49], v[176:177]
	v_pk_mul_f32 v[134:135], v[38:39], v[176:177]
	v_pk_mul_f32 v[136:137], v[40:41], v[176:177]
	v_exp_f32_e32 v130, v130
	v_exp_f32_e32 v131, v131
	v_exp_f32_e32 v132, v132
	v_exp_f32_e32 v133, v133
	v_exp_f32_e32 v134, v134
	v_exp_f32_e32 v135, v135
	v_exp_f32_e32 v136, v136
	v_exp_f32_e32 v137, v137
	v_pk_mul_f32 v[138:139], v[46:47], v[42:43]
	v_pk_mul_f32 v[140:141], v[48:49], v[44:45]
	v_pk_add_f32 v[130:131], v[130:131], 1.0 op_sel_hi:[1,0]
	v_pk_add_f32 v[132:133], v[132:133], 1.0 op_sel_hi:[1,0]
	v_pk_add_f32 v[134:135], v[134:135], 1.0 op_sel_hi:[1,0]
	v_pk_add_f32 v[136:137], v[136:137], 1.0 op_sel_hi:[1,0]
	v_rcp_f32_e32 v130, v130
	v_rcp_f32_e32 v131, v131
	v_rcp_f32_e32 v132, v132
	v_rcp_f32_e32 v133, v133
	v_rcp_f32_e32 v134, v134
	v_rcp_f32_e32 v135, v135
	v_rcp_f32_e32 v136, v136
	v_rcp_f32_e32 v137, v137
	v_pk_mul_f32 v[142:143], v[38:39], v[34:35]
	v_pk_mul_f32 v[144:145], v[40:41], v[36:37]
	v_pk_mul_f32 v[138:139], v[138:139], v[130:131]
	v_pk_mul_f32 v[140:141], v[140:141], v[132:133]
	v_pk_mul_f32 v[142:143], v[142:143], v[134:135]
	v_pk_mul_f32 v[144:145], v[144:145], v[136:137]
	v_cvt_pk_bf16_f32 v164, v138, v139
	v_cvt_pk_bf16_f32 v165, v140, v141
	v_cvt_pk_bf16_f32 v166, v142, v143
	v_cvt_pk_bf16_f32 v167, v144, v145
	global_store_dwordx2 v[172:173], v[164:165], off
	global_store_dwordx2 v[172:173], v[166:167], off offset:32
	v_lshl_add_u64 v[172:173], v[172:173], 0, s[6:7]
	v_pk_mul_f32 v[206:207], v[30:31], v[176:177]
	v_pk_mul_f32 v[208:209], v[32:33], v[176:177]
	v_pk_mul_f32 v[210:211], v[22:23], v[176:177]
	v_pk_mul_f32 v[212:213], v[24:25], v[176:177]
	v_exp_f32_e32 v206, v206
	v_exp_f32_e32 v207, v207
	v_exp_f32_e32 v208, v208
	v_exp_f32_e32 v209, v209
	v_exp_f32_e32 v210, v210
	v_exp_f32_e32 v211, v211
	v_exp_f32_e32 v212, v212
	v_exp_f32_e32 v213, v213
	v_pk_mul_f32 v[214:215], v[30:31], v[26:27]
	v_pk_mul_f32 v[216:217], v[32:33], v[28:29]
	v_pk_add_f32 v[206:207], v[206:207], 1.0 op_sel_hi:[1,0]
	v_pk_add_f32 v[208:209], v[208:209], 1.0 op_sel_hi:[1,0]
	v_pk_add_f32 v[210:211], v[210:211], 1.0 op_sel_hi:[1,0]
	v_pk_add_f32 v[212:213], v[212:213], 1.0 op_sel_hi:[1,0]
	v_rcp_f32_e32 v206, v206
	v_rcp_f32_e32 v207, v207
	v_rcp_f32_e32 v208, v208
	v_rcp_f32_e32 v209, v209
	v_rcp_f32_e32 v210, v210
	v_rcp_f32_e32 v211, v211
	v_rcp_f32_e32 v212, v212
	v_rcp_f32_e32 v213, v213
	v_pk_mul_f32 v[218:219], v[22:23], v[18:19]
	v_pk_mul_f32 v[220:221], v[24:25], v[20:21]
	v_pk_mul_f32 v[214:215], v[214:215], v[206:207]
	v_pk_mul_f32 v[216:217], v[216:217], v[208:209]
	v_pk_mul_f32 v[218:219], v[218:219], v[210:211]
	v_pk_mul_f32 v[220:221], v[220:221], v[212:213]
	v_cvt_pk_bf16_f32 v222, v214, v215
	v_cvt_pk_bf16_f32 v223, v216, v217
	v_cvt_pk_bf16_f32 v224, v218, v219
	v_cvt_pk_bf16_f32 v225, v220, v221
	global_store_dwordx2 v[172:173], v[222:223], off
	global_store_dwordx2 v[172:173], v[224:225], off offset:32
	v_lshl_add_u64 v[172:173], v[172:173], 0, s[6:7]
	v_pk_mul_f32 v[130:131], v[14:15], v[176:177]
	v_pk_mul_f32 v[132:133], v[16:17], v[176:177]
	v_pk_mul_f32 v[134:135], v[6:7], v[176:177]
	v_pk_mul_f32 v[136:137], v[8:9], v[176:177]
	v_exp_f32_e32 v130, v130
	v_exp_f32_e32 v131, v131
	v_exp_f32_e32 v132, v132
	v_exp_f32_e32 v133, v133
	v_exp_f32_e32 v134, v134
	v_exp_f32_e32 v135, v135
	v_exp_f32_e32 v136, v136
	v_exp_f32_e32 v137, v137
	v_pk_mul_f32 v[138:139], v[14:15], v[10:11]
	v_pk_mul_f32 v[140:141], v[16:17], v[12:13]
	v_pk_add_f32 v[130:131], v[130:131], 1.0 op_sel_hi:[1,0]
	v_pk_add_f32 v[132:133], v[132:133], 1.0 op_sel_hi:[1,0]
	v_pk_add_f32 v[134:135], v[134:135], 1.0 op_sel_hi:[1,0]
	v_pk_add_f32 v[136:137], v[136:137], 1.0 op_sel_hi:[1,0]
	v_rcp_f32_e32 v130, v130
	v_rcp_f32_e32 v131, v131
	v_rcp_f32_e32 v132, v132
	v_rcp_f32_e32 v133, v133
	v_rcp_f32_e32 v134, v134
	v_rcp_f32_e32 v135, v135
	v_rcp_f32_e32 v136, v136
	v_rcp_f32_e32 v137, v137
	v_pk_mul_f32 v[142:143], v[6:7], v[2:3]
	v_pk_mul_f32 v[144:145], v[8:9], v[4:5]
	v_pk_mul_f32 v[138:139], v[138:139], v[130:131]
	v_pk_mul_f32 v[140:141], v[140:141], v[132:133]
	v_pk_mul_f32 v[142:143], v[142:143], v[134:135]
	v_pk_mul_f32 v[144:145], v[144:145], v[136:137]
	v_cvt_pk_bf16_f32 v164, v138, v139
	v_cvt_pk_bf16_f32 v165, v140, v141
	v_cvt_pk_bf16_f32 v166, v142, v143
	v_cvt_pk_bf16_f32 v167, v144, v145
	global_store_dwordx2 v[172:173], v[164:165], off
	global_store_dwordx2 v[172:173], v[166:167], off offset:32
	s_branch .LBB0_816
.LBB0_1037:
	s_cmp_lg_u32 s21, 0
	s_cbranch_scc1 .Lswiglu_fast
	s_cselect_b64 s[2:3], -1, 0
	s_lshl_b32 s4, s65, 7
	v_subrev_u32_e32 v146, s4, v162
	v_readlane_b32 s4, v253, 35
	v_ashrrev_i32_e32 v147, 31, v146
	v_mov_b32_e32 v138, 0
	v_mov_b32_e32 v132, s4
	v_readlane_b32 s4, v253, 44
	s_and_b64 vcc, exec, s[2:3]
	v_mov_b32_e32 v139, v138
	v_mov_b32_e32 v0, s4
	ds_read_b64 v[130:131], v0
	v_readlane_b32 s4, v253, 28
	v_mov_b32_e32 v140, v138
	v_mov_b32_e32 v141, v138
	v_mov_b32_e32 v0, s4
	ds_read_b32 v0, v0
	ds_read_b64 v[148:149], v132
	s_waitcnt lgkmcnt(0)
	v_lshl_add_u64 v[130:131], v[146:147], 2, v[130:131]
	s_mov_b64 s[4:5], 0x1000
	v_lshl_add_u64 v[134:135], v[130:131], 0, s[4:5]
	v_mov_b32_e32 v142, v138
	v_mov_b32_e32 v143, v138
	v_mov_b32_e32 v144, v138
	v_mov_b32_e32 v145, v138
	s_cbranch_vccnz .LBB0_1039
	global_load_dwordx4 v[142:145], v[130:131], off
	global_load_dwordx4 v[138:141], v[134:135], off
